# proj main K-loop restructured: one pre/post barrier pair per 64-col K-tile (64 MFMA segments), all fragments of a K-tile in registers, leader half stages B0+A rows 0-63, lagging half stages B1+A rows
# baseline (speedup 1.0000x reference)
; #define PG8_STAGE(bufoff, gbase, voff) do { _Pragma("unroll") for (int _i = 0; _i < 2; ++_i) \
;         __builtin_amdgcn_global_load_lds((const unsigned*)((const char*)(gbase) + (voff)[_i]), (LAS unsigned*)(lds + (bufoff) + ldsw + _i * 8192), 16, 0, 0); } while (0)
; #define PG8_WAIT_V(n) asm volatile("s_waitcnt vmcnt(" #n ")" ::: "memory")
; #define PG8_BAR __builtin_amdgcn_s_barrier()
; template <class Epi, class Order = StaticOrder, bool HALFN = false>
; __device__ __forceinline__ void gemm_phase(LAS unsigned char* lds, const Gemm g, const Epi& E) {
;     ...
;     PG8_STAGE(PG8_SB(0, 0), cB, voffB); PG8_STAGE(PG8_SB(0, 1), cB + hstepB, voffB); PG8_STAGE(PG8_SA(0, 0), cA, voffA); PG8_STAGE(PG8_SA(0, 1), cA + hstepA, voffA);
;     if (wr == 1) PG8_BAR;
;     PG8_WAIT_V(2); PG8_BAR;
;     PG8_STAGE(PG8_SB(1, 0), cB + kstep, voffB); PG8_STAGE(PG8_SA(1, 0), cA + kstep, voffA); PG8_STAGE(PG8_SB(1, 1), cB + hstepB + kstep, voffB);
;     PG8_WAIT_V(6); PG8_BAR;
.LBB0_183:
	s_lshl_b32 s83, s6, 6
	s_lshl_b32 s9, s6, 13
	s_lshl_b32 s6, s7, 5
	s_and_b32 s89, s6, 0x60
	v_lshl_add_u64 v[8:9], v[8:9], 0, s[60:61]
	s_lshl_b32 s16, s89, 7
	s_waitcnt vmcnt(0)
	s_barrier
	v_lshl_add_u64 v[6:7], v[6:7], 0, s[60:61]
	s_add_i32 s95, s53, 0x8000
	s_add_i32 s15, s53, 0xa000
	v_lshl_add_u64 v[2:3], v[2:3], 0, s[60:61]
	s_add_u32 s6, s4, 0x80080
	v_lshl_add_u64 v[2:3], v[4:5], 0, s[60:61]
	s_addc_u32 s7, s5, 0
	v_lshl_add_u64 v[2:3], s[6:7], 0, v[132:133]
	v_lshl_add_u64 v[2:3], s[6:7], 0, v[136:137]
	v_bfe_u32 v143, v10, 4, 2
	v_and_b32_e32 v1, 15, v10
	v_lshlrev_b32_e32 v2, 4, v143
	v_lshlrev_b32_e32 v3, 2, v10
	v_lshl_or_b32 v2, v1, 6, v2
	v_and_b32_e32 v3, 32, v3
	v_bitop3_b32 v4, v2, s9, v3 bitop3:0xde
	v_bitop3_b32 v145, v2, s16, v3 bitop3:0xde
	v_lshlrev_b32_e32 v2, 15, v11
	v_and_b32_e32 v2, 0xffff0000, v2
	v_lshl_add_u32 v2, v12, 12, v2
	v_and_b32_e32 v3, 1, v11
	v_lshl_or_b32 v2, v3, 6, v2
	v_lshl_add_u32 v138, v13, 1, v2
	v_lshlrev_b32_e32 v2, 15, v14
	v_and_b32_e32 v2, 0xffff0000, v2
	s_nop 0
	v_lshl_add_u32 v2, v15, 12, v2
	v_and_b32_e32 v3, 1, v14
	s_cmpk_lt_u32 s8, 0x100
	v_lshl_or_b32 v2, v3, 6, v2
	s_cselect_b64 s[46:47], -1, 0
	s_or_b32 s27, s89, 0xffffdc00
	s_or_b32 s28, s89, 0xfffff400
	s_or_b32 s29, s89, 0x400
	s_or_b32 s16, s89, 0xfffff800
	v_mov_b32_e32 v139, v0
	v_lshl_add_u32 v140, v16, 1, v2
	v_mov_b32_e32 v141, v0
	s_mov_b32 s17, 0
	v_add_u32_e32 v147, 0, v4
	s_and_b64 vcc, exec, s[40:41]
	s_cselect_b32 s23, 0x80000, 0
	s_cselect_b32 s24, 0x4000, 0
	s_mov_b32 s25, 0x20000
	s_cselect_b32 s25, 0xfffe0000, s25
	s_mov_b32 s26, 0x1000
	s_cselect_b32 s26, 0xfffff000, s26
	s_cselect_b32 s6, 0x2000, 0
	v_mov_b32_e32 v206, v130
	s_cbranch_scc0 .Lpj_ldr
	v_mov_b32_e32 v206, v134
.Lpj_ldr:
	v_add_u32_e32 v131, s23, v132
	v_add_u32_e32 v133, s23, v136
	v_add_u32_e32 v135, s25, v131
	v_add_u32_e32 v137, s25, v133
	v_add_u32_e32 v207, s25, v206
	s_add_i32 s15, s53, 0x10000
	s_add_i32 s15, s15, s24
	s_add_i32 s82, s15, s26
	s_add_i32 s95, s53, s6
	s_add_i32 s80, s95, s26
	s_and_b64 vcc, exec, s[40:41]
	s_cbranch_vccz .Lpj_nobar0
	s_barrier
.Lpj_nobar0:
	s_branch .LBB0_186
.LBB0_184:
	s_mov_b64 s[4:5], 0

; #define PG8_STAGE(bufoff, gbase, voff) do { _Pragma("unroll") for (int _i = 0; _i < 2; ++_i) \
;         __builtin_amdgcn_global_load_lds((const unsigned*)((const char*)(gbase) + (voff)[_i]), (LAS unsigned*)(lds + (bufoff) + ldsw + _i * 8192), 16, 0, 0); } while (0)
; #define PG8_LDA(dst, b, h) do { _Pragma("unroll") for (int m = 0; m < 4; ++m) _Pragma("unroll") for (int k = 0; k < 2; ++k) dst[m][k] = *(const LAS bf16x8*)(lds + PG8_SA(b, h) + aoff + m * 2048 + k * 1024); } while (0)
; #define PG8_LDB(dst, b, h) do { _Pragma("unroll") for (int n = 0; n < 2; ++n) _Pragma("unroll") for (int k = 0; k < 2; ++k) dst[n][k] = *(const LAS bf16x8*)(lds + PG8_SB(b, h) + boff + n * 2048 + k * 1024); } while (0)
; #define PG8_SCHED __builtin_amdgcn_sched_barrier(0)
; template <class Epi, class Order = StaticOrder, bool HALFN = false>
; __device__ __forceinline__ void gemm_phase(LAS unsigned char* lds, const Gemm g, const Epi& E) {
;     ...
;         for (int t = 0; t < nt; t += 2) {
;             const bool last = (t == nt - 2);
;             if constexpr (Epi::SEAMS) { if (t == Epi::SEAM0 || t == Epi::SEAM1) E.seam(acc, cur, t == Epi::SEAM0 ? 0 : 1, wr, wc, fr, fq); }
;             const char* a1 = cA + (size_t)(t + 1) * kstep;
;             const char* a2 = last ? nA : cA + (size_t)(t + 2) * kstep; const char* b2 = last ? nB : cB + (size_t)(t + 2) * kstep;
;             const char* a3 = a2 + kstep; const char* b3 = b2 + kstep;
;             PG8_LDB(B0, 0, 0); if constexpr (!HALFN) PG8_LDB(B1, 0, 1); PG8_SCHED; PG8_LDA(At, 0, 0); PG8_STAGE(PG8_SA(1, 1), a1 + hstepA, voffA);
;     ...
; #pragma unroll
;         for (int a = 0; a < 2; ++a)
; #pragma unroll
;             for (int b = 0; b < 2; ++b)
; #pragma unroll
;                 for (int m = 0; m < 4; ++m)
; #pragma unroll
;                     for (int n = 0; n < 2; ++n) acc[a][b][m][n] = (f32x4){0.f, 0.f, 0.f, 0.f};
;         }
;         cur = nxt; cA = nA; cB = nB; ++ui;
.LBB0_193:
	s_mov_b32 s48, s18
	s_ashr_i32 s49, s18, 31
	s_lshl_b64 s[6:7], s[48:49], 20
	s_add_u32 s74, s0, s6
	s_addc_u32 s75, s1, s7
	s_mov_b32 s50, s9
	s_and_b64 s[6:7], s[54:55], exec
	s_cselect_b32 s8, s75, s63
	s_cselect_b32 s9, s74, s62
	s_ashr_i32 s51, s50, 31
	s_lshl_b64 s[6:7], s[50:51], 20
	s_add_u32 s92, s10, s6
	s_addc_u32 s93, s11, s7
	s_and_b64 s[6:7], s[54:55], exec
	s_cselect_b32 s18, s93, s5
	s_cselect_b32 s19, s92, s4
	s_add_u32 s62, s62, 0x80
	s_addc_u32 s63, s63, 0
	s_add_u32 s20, s4, 0x80
	v_mov_b32_e32 v2, 0
	s_addc_u32 s21, s5, 0
	s_mov_b32 s22, 0
	v_add_u32_e32 v142, 0x10000, v145
	v_mov_b32_e32 v3, v2
	v_mov_b32_e32 v4, v2
	v_mov_b32_e32 v5, v2
	v_mov_b32_e32 v6, v2
	v_mov_b32_e32 v7, v2
	v_mov_b32_e32 v8, v2
	v_mov_b32_e32 v9, v2
	v_mov_b32_e32 v10, v2
	v_mov_b32_e32 v11, v2
	v_mov_b32_e32 v12, v2
	v_mov_b32_e32 v13, v2
	v_mov_b32_e32 v18, v2
	v_mov_b32_e32 v19, v2
	v_mov_b32_e32 v20, v2
	v_mov_b32_e32 v21, v2
	v_mov_b32_e32 v26, v2
	v_mov_b32_e32 v27, v2
	v_mov_b32_e32 v28, v2
	v_mov_b32_e32 v29, v2
	v_mov_b32_e32 v34, v2
	v_mov_b32_e32 v35, v2
	v_mov_b32_e32 v36, v2
	v_mov_b32_e32 v37, v2
	v_mov_b32_e32 v42, v2
	v_mov_b32_e32 v43, v2
	v_mov_b32_e32 v44, v2
	v_mov_b32_e32 v45, v2
	v_mov_b32_e32 v50, v2
	v_mov_b32_e32 v51, v2
	v_mov_b32_e32 v52, v2
	v_mov_b32_e32 v53, v2
	v_mov_b32_e32 v14, v2
	v_mov_b32_e32 v15, v2
	v_mov_b32_e32 v16, v2
	v_mov_b32_e32 v17, v2
	v_mov_b32_e32 v22, v2
	v_mov_b32_e32 v23, v2
	v_mov_b32_e32 v24, v2
	v_mov_b32_e32 v25, v2
	v_mov_b32_e32 v30, v2
	v_mov_b32_e32 v31, v2
	v_mov_b32_e32 v32, v2
	v_mov_b32_e32 v33, v2
	v_mov_b32_e32 v38, v2
	v_mov_b32_e32 v39, v2
	v_mov_b32_e32 v40, v2
	v_mov_b32_e32 v41, v2
	v_mov_b32_e32 v46, v2
	v_mov_b32_e32 v47, v2
	v_mov_b32_e32 v48, v2
	v_mov_b32_e32 v49, v2
	v_mov_b32_e32 v54, v2
	v_mov_b32_e32 v55, v2
	v_mov_b32_e32 v56, v2
	v_mov_b32_e32 v57, v2
	v_mov_b32_e32 v58, v2
	v_mov_b32_e32 v59, v2
	v_mov_b32_e32 v60, v2
	v_mov_b32_e32 v61, v2
	v_mov_b32_e32 v62, v2
	v_mov_b32_e32 v63, v2
	v_mov_b32_e32 v64, v2
	v_mov_b32_e32 v65, v2
	v_mov_b32_e32 v66, v2
	v_mov_b32_e32 v67, v2
	v_mov_b32_e32 v68, v2
	v_mov_b32_e32 v69, v2
	v_mov_b32_e32 v70, v2
	v_mov_b32_e32 v71, v2
	v_mov_b32_e32 v72, v2
	v_mov_b32_e32 v73, v2
	v_mov_b32_e32 v74, v2
	v_mov_b32_e32 v75, v2
	v_mov_b32_e32 v76, v2
	v_mov_b32_e32 v77, v2
	v_mov_b32_e32 v82, v2
	v_mov_b32_e32 v83, v2
	v_mov_b32_e32 v84, v2
	v_mov_b32_e32 v85, v2
	v_mov_b32_e32 v90, v2
	v_mov_b32_e32 v91, v2
	v_mov_b32_e32 v92, v2
	v_mov_b32_e32 v93, v2
	v_mov_b32_e32 v98, v2
	v_mov_b32_e32 v99, v2
	v_mov_b32_e32 v100, v2
	v_mov_b32_e32 v101, v2
	v_mov_b32_e32 v110, v2
	v_mov_b32_e32 v111, v2
	v_mov_b32_e32 v112, v2
	v_mov_b32_e32 v113, v2
	v_mov_b32_e32 v118, v2
	v_mov_b32_e32 v119, v2
	v_mov_b32_e32 v120, v2
	v_mov_b32_e32 v121, v2
	v_mov_b32_e32 v78, v2
	v_mov_b32_e32 v79, v2
	v_mov_b32_e32 v80, v2
	v_mov_b32_e32 v81, v2
	v_mov_b32_e32 v86, v2
	v_mov_b32_e32 v87, v2
	v_mov_b32_e32 v88, v2
	v_mov_b32_e32 v89, v2
	v_mov_b32_e32 v94, v2
	v_mov_b32_e32 v95, v2
	v_mov_b32_e32 v96, v2
	v_mov_b32_e32 v97, v2
	v_mov_b32_e32 v102, v2
	v_mov_b32_e32 v103, v2
	v_mov_b32_e32 v104, v2
	v_mov_b32_e32 v105, v2
	v_mov_b32_e32 v106, v2
	v_mov_b32_e32 v107, v2
	v_mov_b32_e32 v108, v2
	v_mov_b32_e32 v109, v2
	v_mov_b32_e32 v114, v2
	v_mov_b32_e32 v115, v2
	v_mov_b32_e32 v116, v2
	v_mov_b32_e32 v117, v2
	v_mov_b32_e32 v122, v2
	v_mov_b32_e32 v123, v2
	v_mov_b32_e32 v124, v2
	v_mov_b32_e32 v125, v2
	v_mov_b32_e32 v126, v2
	v_mov_b32_e32 v127, v2
	v_mov_b32_e32 v128, v2
	v_mov_b32_e32 v129, v2
.Lpj_loop:
	s_add_u32 s4, s62, 0x80
	s_addc_u32 s5, s63, 0
	s_add_u32 s6, s20, 0x80
	s_addc_u32 s7, s21, 0
	s_cmp_eq_u32 s22, 30
	s_cselect_b32 s4, s9, s4
	s_cselect_b32 s5, s8, s5
	s_cselect_b32 s6, s19, s6
	s_cselect_b32 s7, s18, s7
	s_add_u32 s24, s62, 0x80000
	s_addc_u32 s25, s63, 0
	s_add_i32 m0, s15, 0x8000
	ds_read_b128 v[148:151], v142
	global_load_lds_dwordx4 v131, s[20:21]
	s_add_i32 m0, s15, 0xa000
	ds_read_b128 v[152:155], v142 offset:1024
	global_load_lds_dwordx4 v133, s[20:21]
	s_add_i32 m0, s82, 0x8000
	ds_read_b128 v[156:159], v142 offset:2048
	global_load_lds_dwordx4 v135, s[20:21]
	s_add_i32 m0, s82, 0xa000
	ds_read_b128 v[168:171], v142 offset:3072
	global_load_lds_dwordx4 v137, s[20:21]
	s_add_i32 m0, s95, 0x8000
	ds_read_b128 v[208:211], v147
	global_load_lds_dwordx4 v206, s[62:63]
	s_add_i32 m0, s80, 0x8000
	ds_read_b128 v[212:215], v147 offset:1024
	global_load_lds_dwordx4 v207, s[62:63]
	s_add_i32 m0, s95, 0xc000
	ds_read_b128 v[216:219], v147 offset:2048
	global_load_lds_dwordx4 v206, s[24:25]
	s_add_i32 m0, s80, 0xc000
	ds_read_b128 v[220:223], v147 offset:3072
	global_load_lds_dwordx4 v207, s[24:25]
	ds_read_b128 v[224:227], v147 offset:4096
	ds_read_b128 v[228:231], v147 offset:5120
	ds_read_b128 v[232:235], v147 offset:6144
	ds_read_b128 v[236:239], v147 offset:7168
	ds_read_b128 v[160:163], v147 offset:16384
	ds_read_b128 v[164:167], v147 offset:17408
	ds_read_b128 v[194:197], v147 offset:18432
	ds_read_b128 v[198:201], v147 offset:19456
	ds_read_b128 v[202:205], v147 offset:20480
	ds_read_b128 v[240:243], v147 offset:21504
	ds_read_b128 v[244:247], v147 offset:22528
	ds_read_b128 v[138:141], v147 offset:23552
	s_waitcnt lgkmcnt(0)
	s_setprio 1
	s_barrier
; #define PG8_STAGE(bufoff, gbase, voff) do { _Pragma("unroll") for (int _i = 0; _i < 2; ++_i) \
;         __builtin_amdgcn_global_load_lds((const unsigned*)((const char*)(gbase) + (voff)[_i]), (LAS unsigned*)(lds + (bufoff) + ldsw + _i * 8192), 16, 0, 0); } while (0)
; #define PG8_LDA(dst, b, h) do { _Pragma("unroll") for (int m = 0; m < 4; ++m) _Pragma("unroll") for (int k = 0; k < 2; ++k) dst[m][k] = *(const LAS bf16x8*)(lds + PG8_SA(b, h) + aoff + m * 2048 + k * 1024); } while (0)
; #define PG8_LDB(dst, b, h) do { _Pragma("unroll") for (int n = 0; n < 2; ++n) _Pragma("unroll") for (int k = 0; k < 2; ++k) dst[n][k] = *(const LAS bf16x8*)(lds + PG8_SB(b, h) + boff + n * 2048 + k * 1024); } while (0)
; #define PG8_MMA(ai, bj, At, Bt) do { __builtin_amdgcn_s_setprio(1); _Pragma("unroll") for (int m = 0; m < 4; ++m) _Pragma("unroll") for (int n = 0; n < 2; ++n) _Pragma("unroll") for (int k = 0; k < 2; ++k) \
;         acc[ai][bj][m][n] = __builtin_amdgcn_mfma_f32_16x16x32_bf16(Bt[n][k], At[m][k], acc[ai][bj][m][n], 0, 0, 0); __builtin_amdgcn_s_setprio(0); } while (0)
; #define PG8_WAIT_V(n) asm volatile("s_waitcnt vmcnt(" #n ")" ::: "memory")
; #define PG8_WAIT_L(n) asm volatile("s_waitcnt lgkmcnt(" #n ")" ::: "memory")
; #define PG8_BAR __builtin_amdgcn_s_barrier()
; #define PG8_SCHED __builtin_amdgcn_sched_barrier(0)
; template <class Epi, class Order = StaticOrder, bool HALFN = false>
; __device__ __forceinline__ void gemm_phase(LAS unsigned char* lds, const Gemm g, const Epi& E) {
;     ...
;             PG8_LDB(B0, 0, 0); if constexpr (!HALFN) PG8_LDB(B1, 0, 1); PG8_SCHED; PG8_LDA(At, 0, 0); PG8_STAGE(PG8_SA(1, 1), a1 + hstepA, voffA);
;             PG8_WAIT_V(8); PG8_WAIT_L(0); PG8_BAR; PG8_MMA(0, 0, At, B0); if constexpr (!HALFN) PG8_MMA(0, 1, At, B1); PG8_BAR; PG8_SCHED;
;             PG8_LDA(At, 0, 1); PG8_STAGE(PG8_SB(0, 0), b2, voffB); PG8_STAGE(PG8_SB(0, 1), b2 + hstepB, voffB); PG8_STAGE(PG8_SA(0, 0), a2, voffA);
;             PG8_WAIT_V(8); PG8_WAIT_L(0); PG8_BAR; PG8_MMA(1, 0, At, B0); if constexpr (!HALFN) PG8_MMA(1, 1, At, B1); PG8_BAR; PG8_SCHED;
;             PG8_LDB(B0, 1, 0); if constexpr (!HALFN) PG8_LDB(B1, 1, 1); PG8_SCHED; PG8_LDA(At, 1, 0); PG8_STAGE(PG8_SA(0, 1), a2 + hstepA, voffA);
;             PG8_WAIT_V(8); PG8_WAIT_L(0); PG8_BAR; PG8_MMA(0, 0, At, B0); if constexpr (!HALFN) PG8_MMA(0, 1, At, B1); PG8_BAR; PG8_SCHED;
	ds_read_b128 v[172:175], v142 offset:16384
	ds_read_b128 v[176:179], v142 offset:17408
	ds_read_b128 v[180:183], v142 offset:18432
	ds_read_b128 v[184:187], v142 offset:19456
	v_mfma_f32_16x16x32_bf16 v[126:129], v[148:151], v[208:211], v[126:129]
	v_mfma_f32_16x16x32_bf16 v[122:125], v[156:159], v[208:211], v[122:125]
	v_mfma_f32_16x16x32_bf16 v[114:117], v[148:151], v[216:219], v[114:117]
	v_mfma_f32_16x16x32_bf16 v[106:109], v[156:159], v[216:219], v[106:109]
	v_mfma_f32_16x16x32_bf16 v[102:105], v[148:151], v[224:227], v[102:105]
	v_mfma_f32_16x16x32_bf16 v[94:97], v[156:159], v[224:227], v[94:97]
	v_mfma_f32_16x16x32_bf16 v[86:89], v[148:151], v[232:235], v[86:89]
	v_mfma_f32_16x16x32_bf16 v[78:81], v[156:159], v[232:235], v[78:81]
	v_mfma_f32_16x16x32_bf16 v[126:129], v[152:155], v[212:215], v[126:129]
	v_mfma_f32_16x16x32_bf16 v[122:125], v[168:171], v[212:215], v[122:125]
	v_mfma_f32_16x16x32_bf16 v[114:117], v[152:155], v[220:223], v[114:117]
	v_mfma_f32_16x16x32_bf16 v[106:109], v[168:171], v[220:223], v[106:109]
	v_mfma_f32_16x16x32_bf16 v[102:105], v[152:155], v[228:231], v[102:105]
	v_mfma_f32_16x16x32_bf16 v[94:97], v[168:171], v[228:231], v[94:97]
	v_mfma_f32_16x16x32_bf16 v[86:89], v[152:155], v[236:239], v[86:89]
	v_mfma_f32_16x16x32_bf16 v[78:81], v[168:171], v[236:239], v[78:81]
	v_mfma_f32_16x16x32_bf16 v[62:65], v[148:151], v[160:163], v[62:65]
	v_mfma_f32_16x16x32_bf16 v[58:61], v[156:159], v[160:163], v[58:61]
	v_mfma_f32_16x16x32_bf16 v[54:57], v[148:151], v[194:197], v[54:57]
	v_mfma_f32_16x16x32_bf16 v[46:49], v[156:159], v[194:197], v[46:49]
	v_mfma_f32_16x16x32_bf16 v[38:41], v[148:151], v[202:205], v[38:41]
	v_mfma_f32_16x16x32_bf16 v[30:33], v[156:159], v[202:205], v[30:33]
	v_mfma_f32_16x16x32_bf16 v[22:25], v[148:151], v[244:247], v[22:25]
	v_mfma_f32_16x16x32_bf16 v[14:17], v[156:159], v[244:247], v[14:17]
	v_mfma_f32_16x16x32_bf16 v[62:65], v[152:155], v[164:167], v[62:65]
	v_mfma_f32_16x16x32_bf16 v[58:61], v[168:171], v[164:167], v[58:61]
	v_mfma_f32_16x16x32_bf16 v[54:57], v[152:155], v[198:201], v[54:57]
	v_mfma_f32_16x16x32_bf16 v[46:49], v[168:171], v[198:201], v[46:49]
	v_mfma_f32_16x16x32_bf16 v[38:41], v[152:155], v[240:243], v[38:41]
	v_mfma_f32_16x16x32_bf16 v[30:33], v[168:171], v[240:243], v[30:33]
	v_mfma_f32_16x16x32_bf16 v[22:25], v[152:155], v[138:141], v[22:25]
	v_mfma_f32_16x16x32_bf16 v[14:17], v[168:171], v[138:141], v[14:17]
	s_waitcnt lgkmcnt(0)
	v_mfma_f32_16x16x32_bf16 v[118:121], v[172:175], v[208:211], v[118:121]
	v_mfma_f32_16x16x32_bf16 v[110:113], v[180:183], v[208:211], v[110:113]
	v_mfma_f32_16x16x32_bf16 v[98:101], v[172:175], v[216:219], v[98:101]
	v_mfma_f32_16x16x32_bf16 v[90:93], v[180:183], v[216:219], v[90:93]
	v_mfma_f32_16x16x32_bf16 v[82:85], v[172:175], v[224:227], v[82:85]
	v_mfma_f32_16x16x32_bf16 v[74:77], v[180:183], v[224:227], v[74:77]
	v_mfma_f32_16x16x32_bf16 v[70:73], v[172:175], v[232:235], v[70:73]
	v_mfma_f32_16x16x32_bf16 v[66:69], v[180:183], v[232:235], v[66:69]
	v_mfma_f32_16x16x32_bf16 v[118:121], v[176:179], v[212:215], v[118:121]
	v_mfma_f32_16x16x32_bf16 v[110:113], v[184:187], v[212:215], v[110:113]
	v_mfma_f32_16x16x32_bf16 v[98:101], v[176:179], v[220:223], v[98:101]
	v_mfma_f32_16x16x32_bf16 v[90:93], v[184:187], v[220:223], v[90:93]
	v_mfma_f32_16x16x32_bf16 v[82:85], v[176:179], v[228:231], v[82:85]
	v_mfma_f32_16x16x32_bf16 v[74:77], v[184:187], v[228:231], v[74:77]
	v_mfma_f32_16x16x32_bf16 v[70:73], v[176:179], v[236:239], v[70:73]
	v_mfma_f32_16x16x32_bf16 v[66:69], v[184:187], v[236:239], v[66:69]
	v_mfma_f32_16x16x32_bf16 v[50:53], v[172:175], v[160:163], v[50:53]
	v_mfma_f32_16x16x32_bf16 v[42:45], v[180:183], v[160:163], v[42:45]
	v_mfma_f32_16x16x32_bf16 v[34:37], v[172:175], v[194:197], v[34:37]
	v_mfma_f32_16x16x32_bf16 v[26:29], v[180:183], v[194:197], v[26:29]
	v_mfma_f32_16x16x32_bf16 v[18:21], v[172:175], v[202:205], v[18:21]
	v_mfma_f32_16x16x32_bf16 v[10:13], v[180:183], v[202:205], v[10:13]
	v_mfma_f32_16x16x32_bf16 v[6:9], v[172:175], v[244:247], v[6:9]
	v_mfma_f32_16x16x32_bf16 v[2:5], v[180:183], v[244:247], v[2:5]
	v_mfma_f32_16x16x32_bf16 v[50:53], v[176:179], v[164:167], v[50:53]
	v_mfma_f32_16x16x32_bf16 v[42:45], v[184:187], v[164:167], v[42:45]
	v_mfma_f32_16x16x32_bf16 v[34:37], v[176:179], v[198:201], v[34:37]
	v_mfma_f32_16x16x32_bf16 v[26:29], v[184:187], v[198:201], v[26:29]
	v_mfma_f32_16x16x32_bf16 v[18:21], v[176:179], v[240:243], v[18:21]
	v_mfma_f32_16x16x32_bf16 v[10:13], v[184:187], v[240:243], v[10:13]
	v_mfma_f32_16x16x32_bf16 v[6:9], v[176:179], v[138:141], v[6:9]
	v_mfma_f32_16x16x32_bf16 v[2:5], v[184:187], v[138:141], v[2:5]
	s_waitcnt vmcnt(0)
	s_barrier
	s_setprio 0
	s_add_u32 s24, s4, 0x80000
	s_addc_u32 s25, s5, 0
	s_mov_b32 m0, s15
	ds_read_b128 v[148:151], v142 offset:32768
	global_load_lds_dwordx4 v131, s[6:7]
	s_add_i32 m0, s15, 0x2000
	ds_read_b128 v[152:155], v142 offset:33792
	global_load_lds_dwordx4 v133, s[6:7]
	s_mov_b32 m0, s82
	ds_read_b128 v[156:159], v142 offset:34816
	global_load_lds_dwordx4 v135, s[6:7]
	s_add_i32 m0, s82, 0x2000
	ds_read_b128 v[168:171], v142 offset:35840
	global_load_lds_dwordx4 v137, s[6:7]
	s_mov_b32 m0, s95
	ds_read_b128 v[208:211], v147 offset:32768
	global_load_lds_dwordx4 v206, s[4:5]
	s_mov_b32 m0, s80
	ds_read_b128 v[212:215], v147 offset:33792
	global_load_lds_dwordx4 v207, s[4:5]
	s_add_i32 m0, s95, 0x4000
	ds_read_b128 v[216:219], v147 offset:34816
	global_load_lds_dwordx4 v206, s[24:25]
	s_add_i32 m0, s80, 0x4000
	ds_read_b128 v[220:223], v147 offset:35840
	global_load_lds_dwordx4 v207, s[24:25]
	ds_read_b128 v[224:227], v147 offset:36864
	ds_read_b128 v[228:231], v147 offset:37888
	ds_read_b128 v[232:235], v147 offset:38912
	ds_read_b128 v[236:239], v147 offset:39936
	ds_read_b128 v[160:163], v147 offset:49152
	ds_read_b128 v[164:167], v147 offset:50176
	ds_read_b128 v[194:197], v147 offset:51200
	ds_read_b128 v[198:201], v147 offset:52224
	ds_read_b128 v[202:205], v147 offset:53248
	ds_read_b128 v[240:243], v147 offset:54272
	ds_read_b128 v[244:247], v147 offset:55296
	ds_read_b128 v[138:141], v147 offset:56320
	s_waitcnt lgkmcnt(0)
	s_setprio 1
	s_barrier
; #define PG8_STAGE(bufoff, gbase, voff) do { _Pragma("unroll") for (int _i = 0; _i < 2; ++_i) \
;         __builtin_amdgcn_global_load_lds((const unsigned*)((const char*)(gbase) + (voff)[_i]), (LAS unsigned*)(lds + (bufoff) + ldsw + _i * 8192), 16, 0, 0); } while (0)
; #define PG8_LDA(dst, b, h) do { _Pragma("unroll") for (int m = 0; m < 4; ++m) _Pragma("unroll") for (int k = 0; k < 2; ++k) dst[m][k] = *(const LAS bf16x8*)(lds + PG8_SA(b, h) + aoff + m * 2048 + k * 1024); } while (0)
; #define PG8_LDB(dst, b, h) do { _Pragma("unroll") for (int n = 0; n < 2; ++n) _Pragma("unroll") for (int k = 0; k < 2; ++k) dst[n][k] = *(const LAS bf16x8*)(lds + PG8_SB(b, h) + boff + n * 2048 + k * 1024); } while (0)
; #define PG8_MMA(ai, bj, At, Bt) do { __builtin_amdgcn_s_setprio(1); _Pragma("unroll") for (int m = 0; m < 4; ++m) _Pragma("unroll") for (int n = 0; n < 2; ++n) _Pragma("unroll") for (int k = 0; k < 2; ++k) \
;         acc[ai][bj][m][n] = __builtin_amdgcn_mfma_f32_16x16x32_bf16(Bt[n][k], At[m][k], acc[ai][bj][m][n], 0, 0, 0); __builtin_amdgcn_s_setprio(0); } while (0)
; template <class Epi, class Order = StaticOrder, bool HALFN = false>
; __device__ __forceinline__ void gemm_phase(LAS unsigned char* lds, const Gemm g, const Epi& E) {
;     ...
;             PG8_LDB(B0, 1, 0); if constexpr (!HALFN) PG8_LDB(B1, 1, 1); PG8_SCHED; PG8_LDA(At, 1, 0); PG8_STAGE(PG8_SA(0, 1), a2 + hstepA, voffA);
;             PG8_WAIT_V(8); PG8_WAIT_L(0); PG8_BAR; PG8_MMA(0, 0, At, B0); if constexpr (!HALFN) PG8_MMA(0, 1, At, B1); PG8_BAR; PG8_SCHED;
;             PG8_LDA(At, 1, 1); PG8_STAGE(PG8_SB(1, 0), b3, voffB); PG8_STAGE(PG8_SB(1, 1), b3 + hstepB, voffB); PG8_STAGE(PG8_SA(1, 0), a3, voffA);
;             PG8_WAIT_V(8); PG8_WAIT_L(0); PG8_BAR; PG8_MMA(1, 0, At, B0); if constexpr (!HALFN) PG8_MMA(1, 1, At, B1); PG8_BAR; PG8_SCHED;
;         }
;     __device__ __forceinline__ void operator()(f32x4 (&acc)[2][2][4][2], const Unit& u, int wr, int wc, int fr, int fq) const {
;     ...
; #pragma unroll
;         for (int ai = 0; ai < 2; ++ai)
; #pragma unroll
;             for (int m = 0; m < 4; ++m) rsv[ai][m] = ssq[u.pm * 256 + ai * 128 + wr * 64 + m * 16 + fr];
;         asm volatile("" ::: "memory");
; #pragma unroll
;         for (int ai = 0; ai < 2; ++ai)
; #pragma unroll
;             for (int m = 0; m < 4; ++m) rsv[ai][m] = __builtin_amdgcn_rsqf(rsv[ai][m] * (1.0f / DM) + RMS_EPS);
	ds_read_b128 v[172:175], v142 offset:49152
	ds_read_b128 v[176:179], v142 offset:50176
	ds_read_b128 v[180:183], v142 offset:51200
	ds_read_b128 v[184:187], v142 offset:52224
	v_mfma_f32_16x16x32_bf16 v[126:129], v[148:151], v[208:211], v[126:129]
	v_mfma_f32_16x16x32_bf16 v[122:125], v[156:159], v[208:211], v[122:125]
	v_mfma_f32_16x16x32_bf16 v[114:117], v[148:151], v[216:219], v[114:117]
	v_mfma_f32_16x16x32_bf16 v[106:109], v[156:159], v[216:219], v[106:109]
	v_mfma_f32_16x16x32_bf16 v[102:105], v[148:151], v[224:227], v[102:105]
	v_mfma_f32_16x16x32_bf16 v[94:97], v[156:159], v[224:227], v[94:97]
	v_mfma_f32_16x16x32_bf16 v[86:89], v[148:151], v[232:235], v[86:89]
	v_mfma_f32_16x16x32_bf16 v[78:81], v[156:159], v[232:235], v[78:81]
	v_mfma_f32_16x16x32_bf16 v[126:129], v[152:155], v[212:215], v[126:129]
	v_mfma_f32_16x16x32_bf16 v[122:125], v[168:171], v[212:215], v[122:125]
	v_mfma_f32_16x16x32_bf16 v[114:117], v[152:155], v[220:223], v[114:117]
	v_mfma_f32_16x16x32_bf16 v[106:109], v[168:171], v[220:223], v[106:109]
	v_mfma_f32_16x16x32_bf16 v[102:105], v[152:155], v[228:231], v[102:105]
	v_mfma_f32_16x16x32_bf16 v[94:97], v[168:171], v[228:231], v[94:97]
	v_mfma_f32_16x16x32_bf16 v[86:89], v[152:155], v[236:239], v[86:89]
	v_mfma_f32_16x16x32_bf16 v[78:81], v[168:171], v[236:239], v[78:81]
	v_mfma_f32_16x16x32_bf16 v[62:65], v[148:151], v[160:163], v[62:65]
	v_mfma_f32_16x16x32_bf16 v[58:61], v[156:159], v[160:163], v[58:61]
	v_mfma_f32_16x16x32_bf16 v[54:57], v[148:151], v[194:197], v[54:57]
	v_mfma_f32_16x16x32_bf16 v[46:49], v[156:159], v[194:197], v[46:49]
	v_mfma_f32_16x16x32_bf16 v[38:41], v[148:151], v[202:205], v[38:41]
	v_mfma_f32_16x16x32_bf16 v[30:33], v[156:159], v[202:205], v[30:33]
	v_mfma_f32_16x16x32_bf16 v[22:25], v[148:151], v[244:247], v[22:25]
	v_mfma_f32_16x16x32_bf16 v[14:17], v[156:159], v[244:247], v[14:17]
	v_mfma_f32_16x16x32_bf16 v[62:65], v[152:155], v[164:167], v[62:65]
	v_mfma_f32_16x16x32_bf16 v[58:61], v[168:171], v[164:167], v[58:61]
	v_mfma_f32_16x16x32_bf16 v[54:57], v[152:155], v[198:201], v[54:57]
	v_mfma_f32_16x16x32_bf16 v[46:49], v[168:171], v[198:201], v[46:49]
	v_mfma_f32_16x16x32_bf16 v[38:41], v[152:155], v[240:243], v[38:41]
	v_mfma_f32_16x16x32_bf16 v[30:33], v[168:171], v[240:243], v[30:33]
	v_mfma_f32_16x16x32_bf16 v[22:25], v[152:155], v[138:141], v[22:25]
	v_mfma_f32_16x16x32_bf16 v[14:17], v[168:171], v[138:141], v[14:17]
	s_waitcnt lgkmcnt(0)
	v_mfma_f32_16x16x32_bf16 v[118:121], v[172:175], v[208:211], v[118:121]
	v_mfma_f32_16x16x32_bf16 v[110:113], v[180:183], v[208:211], v[110:113]
	v_mfma_f32_16x16x32_bf16 v[98:101], v[172:175], v[216:219], v[98:101]
	v_mfma_f32_16x16x32_bf16 v[90:93], v[180:183], v[216:219], v[90:93]
	v_mfma_f32_16x16x32_bf16 v[82:85], v[172:175], v[224:227], v[82:85]
	v_mfma_f32_16x16x32_bf16 v[74:77], v[180:183], v[224:227], v[74:77]
	v_mfma_f32_16x16x32_bf16 v[70:73], v[172:175], v[232:235], v[70:73]
	v_mfma_f32_16x16x32_bf16 v[66:69], v[180:183], v[232:235], v[66:69]
	v_mfma_f32_16x16x32_bf16 v[118:121], v[176:179], v[212:215], v[118:121]
	v_mfma_f32_16x16x32_bf16 v[110:113], v[184:187], v[212:215], v[110:113]
	v_mfma_f32_16x16x32_bf16 v[98:101], v[176:179], v[220:223], v[98:101]
	v_mfma_f32_16x16x32_bf16 v[90:93], v[184:187], v[220:223], v[90:93]
	v_mfma_f32_16x16x32_bf16 v[82:85], v[176:179], v[228:231], v[82:85]
	v_mfma_f32_16x16x32_bf16 v[74:77], v[184:187], v[228:231], v[74:77]
	v_mfma_f32_16x16x32_bf16 v[70:73], v[176:179], v[236:239], v[70:73]
	v_mfma_f32_16x16x32_bf16 v[66:69], v[184:187], v[236:239], v[66:69]
	v_mfma_f32_16x16x32_bf16 v[50:53], v[172:175], v[160:163], v[50:53]
	v_mfma_f32_16x16x32_bf16 v[42:45], v[180:183], v[160:163], v[42:45]
	v_mfma_f32_16x16x32_bf16 v[34:37], v[172:175], v[194:197], v[34:37]
	v_mfma_f32_16x16x32_bf16 v[26:29], v[180:183], v[194:197], v[26:29]
	v_mfma_f32_16x16x32_bf16 v[18:21], v[172:175], v[202:205], v[18:21]
	v_mfma_f32_16x16x32_bf16 v[10:13], v[180:183], v[202:205], v[10:13]
	v_mfma_f32_16x16x32_bf16 v[6:9], v[172:175], v[244:247], v[6:9]
	v_mfma_f32_16x16x32_bf16 v[2:5], v[180:183], v[244:247], v[2:5]
	v_mfma_f32_16x16x32_bf16 v[50:53], v[176:179], v[164:167], v[50:53]
	v_mfma_f32_16x16x32_bf16 v[42:45], v[184:187], v[164:167], v[42:45]
	v_mfma_f32_16x16x32_bf16 v[34:37], v[176:179], v[198:201], v[34:37]
	v_mfma_f32_16x16x32_bf16 v[26:29], v[184:187], v[198:201], v[26:29]
	v_mfma_f32_16x16x32_bf16 v[18:21], v[176:179], v[240:243], v[18:21]
	v_mfma_f32_16x16x32_bf16 v[10:13], v[184:187], v[240:243], v[10:13]
	v_mfma_f32_16x16x32_bf16 v[6:9], v[176:179], v[138:141], v[6:9]
	v_mfma_f32_16x16x32_bf16 v[2:5], v[184:187], v[138:141], v[2:5]
	s_waitcnt vmcnt(0)
	s_barrier
	s_setprio 0
	s_add_i32 s22, s22, 2
	s_add_u32 s62, s62, 0x100
	s_addc_u32 s63, s63, 0
	s_add_u32 s20, s20, 0x100
	s_addc_u32 s21, s21, 0
	s_cmp_lt_u32 s22, 32
	s_cbranch_scc1 .Lpj_loop
	s_and_b64 vcc, exec, s[46:47]
	s_cbranch_vccz .LBB0_197
	s_barrier
.LBB0_197:
	v_mov_b64_e32 v[162:163], 0x6ff
	s_lshl_b32 s4, s94, 8
	v_mov_b32_e32 v142, v1
	v_mov_b32_e32 v210, v143
	s_add_i32 s4, s4, s83
	s_cmp_gt_i32 s52, 7
	v_add_u32_e32 v154, s4, v142
	v_ashrrev_i32_e32 v155, 31, v154
	v_lshl_add_u64 v[148:149], v[154:155], 2, s[44:45]
	global_load_dword v142, v[148:149], off
	global_load_dword v144, v[148:149], off offset:64
	global_load_dword v146, v[148:149], off offset:128
	global_load_dword v150, v[148:149], off offset:192
	global_load_dword v152, v[148:149], off offset:512
	global_load_dword v156, v[148:149], off offset:576
	global_load_dword v158, v[148:149], off offset:640
	s_nop 0
	global_load_dword v148, v[148:149], off offset:704
	v_add_u32_e32 v209, 16, v154
	v_add_u32_e32 v208, 32, v154
	v_add_u32_e32 v157, 48, v154
	v_add_u32_e32 v155, 0x80, v154
	v_add_u32_e32 v153, 0x90, v154
	v_add_u32_e32 v151, 0xa0, v154
	v_add_u32_e32 v149, 0xb0, v154
	s_mov_b64 s[4:5], -1
	s_waitcnt vmcnt(0)
	v_fmamk_f32 v142, v142, 0x3a000000, v189
	v_fmamk_f32 v144, v144, 0x3a000000, v189
	v_fmamk_f32 v146, v146, 0x3a000000, v189
	v_fmamk_f32 v150, v150, 0x3a000000, v189
	v_fmamk_f32 v159, v152, 0x3a000000, v189
	v_fmamk_f32 v160, v156, 0x3a000000, v189
	v_fmamk_f32 v161, v158, 0x3a000000, v189
	v_fmamk_f32 v168, v148, 0x3a000000, v189
	v_rsq_f32_e32 v158, v142
	v_rsq_f32_e32 v156, v144
	v_rsq_f32_e32 v152, v146
	v_rsq_f32_e32 v150, v150
	v_rsq_f32_e32 v148, v159
	v_rsq_f32_e32 v146, v160
	v_rsq_f32_e32 v144, v161
	v_rsq_f32_e32 v142, v168
	s_cbranch_scc1 .LBB0_200
	s_andn2_b64 vcc, exec, s[4:5]
	s_cbranch_vccz .LBB0_221

; #define PG8_WAIT_V(n) asm volatile("s_waitcnt vmcnt(" #n ")" ::: "memory")
; #define PG8_BAR __builtin_amdgcn_s_barrier()
; template <class Epi, class Order = StaticOrder, bool HALFN = false>
; __device__ __forceinline__ void gemm_phase(LAS unsigned char* lds, const Gemm g, const Epi& E) {
;     ...
;     PG8_WAIT_V(0);
;     PG8_BAR;
; template <int W>
; __device__ __forceinline__ void pool_branch(const bf16_t* __restrict__ Pb, bf16_t* __restrict__ out, bool first) {
;     ...
;         const float inv = (first && (i + 1 < W)) ? 1.0f / (float)(i + 1) : 1.0f / (float)W;
.LBB0_224:
	v_mov_b64_e32 v[164:165], 0xff
	v_mov_b64_e32 v[166:167], 0x7f
	v_mov_b32_e32 v193, 0x1800
	v_mov_b32_e32 v194, 0x3e000000
	v_mov_b32_e32 v195, 0x3eaaaaab
	v_mov_b32_e32 v196, 0x3e800000
	v_mov_b32_e32 v197, 0x3e4ccccd
	v_mov_b32_e32 v198, 0x3e2aaaab
	v_mov_b32_e32 v199, 0x3e124925
	v_mov_b32_e32 v200, 0x3d800000
	v_mov_b32_e32 v201, 0x3de38e39
	v_mov_b32_e32 v202, 0x3dcccccd
	v_mov_b32_e32 v203, 0x3dba2e8c
	v_mov_b32_e32 v204, 0x3daaaaab
	v_mov_b32_e32 v205, 0x3d9d89d9
	v_mov_b32_e32 v206, 0x3d924925
	v_mov_b32_e32 v207, 0x3d888889
	s_waitcnt vmcnt(0)
	s_barrier
